# P2 NA strip prologue: bias-table load issued ahead of the K/V fill (index clamped instead of EXEC-masked) rather than after the fill drained, then waited alone
# baseline (speedup 1.0000x reference)
; #define LAS __attribute__((address_space(3)))
; __device__ __forceinline__ void na_strip(const Params& P, LAS unsigned char* lds, int strip, int hsel, int tid, int lane, int wave) {
;     ...
;         const int lo = na_start(r0, rows);
;         u32x4 kr[9], vr[9];
; #pragma unroll
;         for (int i = 0; i < 9; ++i) { const int row = min(lo + i, rows - 1); const size_t o = ((size_t)sq0 + (size_t)row * 64) * 512 + ssrc; kr[i] = *(const u32x4*)(KA + o); vr[i] = *(const u32x4*)(VA + o); }
; #pragma unroll
;         for (int i = 0; i < 9; ++i) { const int row = min(lo + i, rows - 1); const unsigned sl = (unsigned)(row % 9) * 8192u;
;             if (lo + i < rows) { *(LAS u32x4*)(lds + sl + kdst) = kr[i]; *(LAS u32x4*)(lds + sl + vdst) = vr[i]; } }
;         LAS float* rpbs = (LAS float*)(lds + NA_RPB);
;         for (int i = tid; i < 465; i += 512) rpbs[i] = P.rpb[h * 465 + i] * LOG2E;
.LBB0_279:
	s_bitcmp1_b32 s74, 0
	s_cselect_b64 s[6:7], -1, 0
	s_and_b64 s[6:7], s[4:5], s[6:7]
	s_or_b32 s12, s11, 8
	s_and_b64 s[6:7], s[6:7], exec
	s_cselect_b32 s76, s12, s11
	v_sub_u32_e64 v2, s76, 4 clamp
	s_add_i32 s77, s75, -8
	v_readfirstlane_b32 s6, v2
	s_lshl_b32 s25, s10, 6
	s_min_u32 s17, s6, s77
	v_add_u32_e32 v70, s25, v79
	s_add_i32 s18, s75, -1
	s_lshl_b32 s48, s26, 9
	s_or_b32 s16, s17, 1
	v_lshl_add_u64 v[94:95], s[48:49], 0, v[70:71]
	s_min_u32 s48, s16, s18
	s_lshl_b64 s[6:7], s[48:49], 15
	v_lshl_add_u64 v[2:3], s[6:7], 0, v[94:95]
	s_or_b32 s15, s17, 2
	v_lshlrev_b64 v[2:3], 1, v[2:3]
	s_min_u32 s48, s15, s18
	v_lshl_add_u64 v[4:5], s[44:45], 0, v[2:3]
	v_lshl_add_u64 v[2:3], s[46:47], 0, v[2:3]
	s_lshl_b64 s[6:7], s[48:49], 15
	s_add_i32 s80, s76, s52
	s_mov_b32 s81, 0
	s_lshl_b64 s[80:81], s[80:81], 16
	s_add_u32 s80, s42, s80
	s_addc_u32 s81, s43, s81
	v_add_u32_e32 v242, s26, v103
	v_lshlrev_b32_e32 v242, 10, v242
	v_mov_b32_e32 v243, 0
	v_lshl_add_u64 v[242:243], s[80:81], 0, v[242:243]
	s_lshl_b32 s82, s25, 1
	s_mov_b32 s83, 0
	v_lshl_add_u64 v[242:243], v[242:243], 0, s[82:83]
	v_lshlrev_b32_e32 v244, 1, v68
	v_mov_b32_e32 v245, 0
	v_lshl_add_u64 v[242:243], v[242:243], 0, v[244:245]
	global_load_dwordx4 v[246:249], v[242:243], off offset:64
	global_load_dwordx4 v[242:245], v[242:243], off
	s_mul_i32 s84, s10, 0x1d1
	v_min_u32_e32 v252, 0x1d0, v0
	v_add_u32_e32 v252, s84, v252
	v_mov_b32_e32 v253, 0
	v_lshl_add_u64 v[252:253], v[252:253], 2, s[56:57]
	global_load_dword v251, v[252:253], off
	global_load_dwordx4 v[62:65], v[4:5], off
	global_load_dwordx4 v[58:61], v[2:3], off
	v_lshl_add_u64 v[2:3], s[6:7], 0, v[94:95]
	s_or_b32 s14, s17, 3
	v_lshlrev_b64 v[2:3], 1, v[2:3]
	s_min_u32 s48, s14, s18
	v_lshl_add_u64 v[4:5], s[44:45], 0, v[2:3]
	v_lshl_add_u64 v[2:3], s[46:47], 0, v[2:3]
	s_lshl_b64 s[6:7], s[48:49], 15
	global_load_dwordx4 v[54:57], v[4:5], off
	global_load_dwordx4 v[50:53], v[2:3], off
	v_lshl_add_u64 v[2:3], s[6:7], 0, v[94:95]
	s_add_i32 s13, s17, 4
	v_lshlrev_b64 v[2:3], 1, v[2:3]
	s_min_u32 s48, s13, s18
	v_lshl_add_u64 v[4:5], s[44:45], 0, v[2:3]
	v_lshl_add_u64 v[2:3], s[46:47], 0, v[2:3]
	s_lshl_b64 s[6:7], s[48:49], 15
	global_load_dwordx4 v[46:49], v[4:5], off
	global_load_dwordx4 v[42:45], v[2:3], off
	v_lshl_add_u64 v[2:3], s[6:7], 0, v[94:95]
	s_add_i32 s12, s17, 5
	v_lshlrev_b64 v[2:3], 1, v[2:3]
	s_min_u32 s48, s12, s18
	v_lshl_add_u64 v[4:5], s[44:45], 0, v[2:3]
	v_lshl_add_u64 v[2:3], s[46:47], 0, v[2:3]
	s_lshl_b64 s[6:7], s[48:49], 15
	global_load_dwordx4 v[38:41], v[4:5], off
	global_load_dwordx4 v[34:37], v[2:3], off
	v_lshl_add_u64 v[2:3], s[6:7], 0, v[94:95]
	s_add_i32 s11, s17, 6
	v_lshlrev_b64 v[2:3], 1, v[2:3]
	s_min_u32 s48, s11, s18
	v_lshl_add_u64 v[4:5], s[44:45], 0, v[2:3]
	v_lshl_add_u64 v[2:3], s[46:47], 0, v[2:3]
	s_lshl_b64 s[6:7], s[48:49], 15
	global_load_dwordx4 v[30:33], v[4:5], off
	global_load_dwordx4 v[26:29], v[2:3], off
	v_lshl_add_u64 v[2:3], s[6:7], 0, v[94:95]
	s_add_i32 s7, s17, 7
	v_lshlrev_b64 v[2:3], 1, v[2:3]
	s_min_u32 s48, s7, s18
	v_lshl_add_u64 v[4:5], s[44:45], 0, v[2:3]
	v_lshl_add_u64 v[2:3], s[46:47], 0, v[2:3]
	s_lshl_b64 s[20:21], s[48:49], 15
	global_load_dwordx4 v[22:25], v[4:5], off
	global_load_dwordx4 v[18:21], v[2:3], off
	v_lshl_add_u64 v[2:3], s[20:21], 0, v[94:95]
	s_add_i32 s6, s17, 8
	v_lshlrev_b64 v[2:3], 1, v[2:3]
	s_min_u32 s48, s6, s18
	v_lshl_add_u64 v[4:5], s[44:45], 0, v[2:3]
	v_lshl_add_u64 v[2:3], s[46:47], 0, v[2:3]
	s_lshl_b64 s[20:21], s[48:49], 15
	global_load_dwordx4 v[14:17], v[4:5], off
	global_load_dwordx4 v[10:13], v[2:3], off
	v_lshl_add_u64 v[2:3], s[20:21], 0, v[94:95]
	v_lshlrev_b64 v[2:3], 1, v[2:3]
	v_lshl_add_u64 v[4:5], s[44:45], 0, v[2:3]
	v_lshl_add_u64 v[2:3], s[46:47], 0, v[2:3]
	global_load_dwordx4 v[6:9], v[4:5], off
	s_nop 0
	global_load_dwordx4 v[2:5], v[2:3], off
	s_cmp_lt_u32 s17, s75
	s_cbranch_scc1 .LBB0_317
	s_cmp_ge_u32 s16, s75
	s_cbranch_scc0 .LBB0_318

; #define LAS __attribute__((address_space(3)))
; __device__ __forceinline__ void na_strip(const Params& P, LAS unsigned char* lds, int strip, int hsel, int tid, int lane, int wave) {
;     ...
;         LAS float* rpbs = (LAS float*)(lds + NA_RPB);
;         for (int i = tid; i < 465; i += 512) rpbs[i] = P.rpb[h * 465 + i] * LOG2E;
.LBB0_289:
	s_mulk_i32 s10, 0x1d1
	v_add_u32_e32 v70, s10, v0
	s_waitcnt vmcnt(0)
	v_mul_f32_e32 v2, 0x3fb8aa3b, v251
	ds_write_b32 v83, v2
